# attention: rounds walk down the grid (rows 2*qr+24-8*round) so each of the 4 workgroups of a head first-touches two of a round's new K/V rows, on top of v34
# baseline (speedup 1.0000x reference)
; #define LAS __attribute__((address_space(3)))
; __global__ void __launch_bounds__(NTHREADS, 2) mega(Args args) {
;     ...
;                 for (int it = vcu; it < BATCH * NH * 4; it += G) { const int qr = it & 3, h = (it >> 2) & 15, b = it >> 6;
;                     __syncthreads();
;                     { const int oc0 = (ML + b * CTX) >> 3;
;                       for (int ci = tid; ci < 4096; ci += NTHREADS) { const int o = ci >> 7, wq = ci & 127;
;                           const u32x4 kv = *(const u32x4*)(KTp + ((size_t)((oc0 + o) * NH + h)) * 1024 + wq * 8);
;                           *(LAS u32x4*)(lds + o * 2048 + (wq & ~15) * 16 + ((wq & 15) ^ (o & 2)) * 16) = kv;
;                           const u32x4 vv = *(const u32x4*)(VTp + ((size_t)((oc0 + o) * NH + h)) * 1024 + wq * 8);
;                           *(LAS u32x4*)(lds + 65536 + o * 2048 + wq * 16) = vv; }
;                       LAS float* rp = (LAS float*)(lds + LDS_MISC + 1024);
;                       for (int i = tid; i < 465; i += NTHREADS) rp[i] = rpg[h * 465 + i]; }
;                     __syncthreads();
; #pragma unroll 1
;                     for (int rd = 0; rd < 4; ++rd) attn_unit<true>(Qb, KTp, VTp, Ob, lds, b, h, 8 * qr + 2 * rd + (wave >> 2), wave & 3, 0, lane);
.LBB9_672:
	s_or_b64 exec, exec, s[50:51]
	s_and_b32 s5, s69, 3
	s_lshl_b32 s34, s5, 7
	s_lshl_b32 s5, s5, 1
	s_lshl_b32 s4, s4, 11
	s_add_i32 s50, s66, s5
	s_lshl_b32 s48, s72, 8
	v_add_u32_e32 v157, s4, v167
	s_or_b32 s4, s34, s4
	s_sub_i32 s51, s68, s5
	s_lshl_b32 s33, s72, 7
	v_lshl_add_u64 v[158:159], v[144:145], 0, s[48:49]
	v_lshl_add_u64 v[160:161], v[150:151], 0, s[48:49]
	v_add_u32_e32 v162, s4, v193
	s_mov_b32 s48, 0
	s_mov_b32 s52, s50
	s_mov_b32 s80, -8
	s_add_i32 s52, s52, 24
	s_add_i32 s51, s51, -24
	v_add_u32_e32 v162, 0x600, v162
	s_waitcnt lgkmcnt(0)
	s_barrier
	s_branch .LBB9_674
